# strict K-loop waits relaxed from vmcnt(4) to vmcnt(6): only the first-issued op of the previous segment must have landed
# speedup vs baseline: 1.0068x; 1.0068x over previous
.LBB0_415:
	v_writelane_b32 v250, s5, 0
	v_writelane_b32 v250, s23, 1
	v_writelane_b32 v250, s26, 2
	v_writelane_b32 v250, s27, 3
	v_writelane_b32 v250, s28, 4
	v_writelane_b32 v250, s29, 5
	v_writelane_b32 v250, s42, 6
	v_writelane_b32 v250, s43, 7
	v_writelane_b32 v250, s44, 8
	v_writelane_b32 v250, s45, 9
	v_writelane_b32 v250, s46, 10
	v_writelane_b32 v250, s47, 11
	v_writelane_b32 v250, s48, 12
	v_writelane_b32 v250, s49, 13
	v_writelane_b32 v250, s50, 14
	v_writelane_b32 v250, s51, 15
	v_writelane_b32 v250, s53, 16
	v_writelane_b32 v250, s54, 17
	v_writelane_b32 v250, s55, 18
	v_writelane_b32 v250, s56, 19
	v_writelane_b32 v250, s57, 20
	v_writelane_b32 v250, s58, 21
	v_writelane_b32 v250, s59, 22
	v_writelane_b32 v250, s60, 23
	v_writelane_b32 v250, s61, 24
	v_writelane_b32 v250, s63, 25
	v_writelane_b32 v250, s64, 26
	v_writelane_b32 v250, s65, 27
	s_add_i32 s53, s90, 0x80
	s_add_i32 s54, s52, -4
	s_add_i32 s55, s52, -3
	s_mov_b32 s56, s48
	s_add_i32 s57, s56, 0x2000
	s_add_i32 s58, s56, 0x4000
	s_add_i32 s59, s56, 0x6000
	s_add_i32 s60, s56, 0x8000
	s_add_i32 s61, s56, 0xa000
	v_readfirstlane_b32 s42, v6
	v_readfirstlane_b32 s43, v7
	v_readfirstlane_b32 s28, v4
	v_readfirstlane_b32 s29, v5
	v_readfirstlane_b32 s26, v146
	v_readfirstlane_b32 s5, v147
	v_readfirstlane_b32 s27, v148
	v_readfirstlane_b32 s23, v149
	s_add_u32 s28, s28, 0x100
	s_addc_u32 s29, s29, 0
	s_mov_b32 s63, -2
	v_mov_b32_e32 v4, 0
	s_add_u32 s44, s42, 0x100
	s_addc_u32 s45, s43, 0
	s_cmp_eq_u32 s63, s54
	s_cselect_b32 s50, s26, s44
	s_cselect_b32 s51, s5, s45
	s_cselect_b32 s48, s27, s28
	s_cselect_b32 s49, s23, s29
	s_add_i32 s64, 0, 0x10000
	v_add_u32_e32 v187, s64, v3
	s_add_i32 s65, 0, 0x14000
	ds_read_b128 v[164:167], v187
	ds_read_b128 v[168:171], v187 offset:1024
	ds_read_b128 v[188:191], v187 offset:2048
	ds_read_b128 v[192:195], v187 offset:3072
	v_add_u32_e32 v187, s65, v3
	ds_read_b128 v[196:199], v187
	ds_read_b128 v[200:203], v187 offset:1024
	ds_read_b128 v[204:207], v187 offset:2048
	ds_read_b128 v[208:211], v187 offset:3072
	s_add_u32 s46, s42, 0x80
	s_addc_u32 s47, s43, 0
	s_add_u32 s42, s42, s53
	s_addc_u32 s43, s43, 0
	s_mov_b32 m0, s60
	s_nop 0
	global_load_lds_dwordx4 v0, s[46:47]
	s_mov_b32 m0, s61
	s_nop 0
	global_load_lds_dwordx4 v142, s[46:47]
	s_add_i32 m0, s56, 0xc000
	s_nop 0
	global_load_lds_dwordx4 v0, s[42:43]
	s_add_i32 m0, s56, 0xe000
	s_nop 0
	global_load_lds_dwordx4 v142, s[42:43]
	ds_read_b128 v[212:215], v160
	ds_read_b128 v[216:219], v160 offset:1024
	ds_read_b128 v[220:223], v160 offset:2048
	ds_read_b128 v[224:227], v160 offset:3072
	ds_read_b128 v[228:231], v160 offset:4096
	ds_read_b128 v[232:235], v160 offset:5120
	ds_read_b128 v[236:239], v160 offset:6144
	ds_read_b128 v[240:243], v160 offset:7168
	s_waitcnt vmcnt(8)
	s_waitcnt lgkmcnt(8)
	s_barrier
	s_setprio 1
	s_waitcnt lgkmcnt(0)
	v_mfma_f32_16x16x32_bf16 v[128:131], v[164:167], v[212:215], 0
	v_mfma_f32_16x16x32_bf16 v[124:127], v[188:191], v[212:215], 0
	v_mfma_f32_16x16x32_bf16 v[112:115], v[164:167], v[220:223], 0
	v_mfma_f32_16x16x32_bf16 v[108:111], v[188:191], v[220:223], 0
	v_mfma_f32_16x16x32_bf16 v[96:99], v[164:167], v[228:231], 0
	v_mfma_f32_16x16x32_bf16 v[92:95], v[188:191], v[228:231], 0
	v_mfma_f32_16x16x32_bf16 v[80:83], v[164:167], v[236:239], 0
	v_mfma_f32_16x16x32_bf16 v[76:79], v[188:191], v[236:239], 0
	v_mfma_f32_16x16x32_bf16 v[128:131], v[168:171], v[216:219], v[128:131]
	v_mfma_f32_16x16x32_bf16 v[124:127], v[192:195], v[216:219], v[124:127]
	v_mfma_f32_16x16x32_bf16 v[112:115], v[168:171], v[224:227], v[112:115]
	v_mfma_f32_16x16x32_bf16 v[108:111], v[192:195], v[224:227], v[108:111]
	v_mfma_f32_16x16x32_bf16 v[96:99], v[168:171], v[232:235], v[96:99]
	v_mfma_f32_16x16x32_bf16 v[92:95], v[192:195], v[232:235], v[92:95]
	v_mfma_f32_16x16x32_bf16 v[80:83], v[168:171], v[240:243], v[80:83]
	v_mfma_f32_16x16x32_bf16 v[76:79], v[192:195], v[240:243], v[76:79]
	s_setprio 0
	s_setprio 1
	v_mfma_f32_16x16x32_bf16 v[120:123], v[196:199], v[212:215], 0
	v_mfma_f32_16x16x32_bf16 v[116:119], v[204:207], v[212:215], 0
	v_mfma_f32_16x16x32_bf16 v[104:107], v[196:199], v[220:223], 0
	v_mfma_f32_16x16x32_bf16 v[100:103], v[204:207], v[220:223], 0
	v_mfma_f32_16x16x32_bf16 v[88:91], v[196:199], v[228:231], 0
	v_mfma_f32_16x16x32_bf16 v[84:87], v[204:207], v[228:231], 0
	v_mfma_f32_16x16x32_bf16 v[72:75], v[196:199], v[236:239], 0
	v_mfma_f32_16x16x32_bf16 v[68:71], v[204:207], v[236:239], 0
	v_mfma_f32_16x16x32_bf16 v[120:123], v[200:203], v[216:219], v[120:123]
	v_mfma_f32_16x16x32_bf16 v[116:119], v[208:211], v[216:219], v[116:119]
	v_mfma_f32_16x16x32_bf16 v[104:107], v[200:203], v[224:227], v[104:107]
	v_mfma_f32_16x16x32_bf16 v[100:103], v[208:211], v[224:227], v[100:103]
	v_mfma_f32_16x16x32_bf16 v[88:91], v[200:203], v[232:235], v[88:91]
	v_mfma_f32_16x16x32_bf16 v[84:87], v[208:211], v[232:235], v[84:87]
	v_mfma_f32_16x16x32_bf16 v[72:75], v[200:203], v[240:243], v[72:75]
	v_mfma_f32_16x16x32_bf16 v[68:71], v[208:211], v[240:243], v[68:71]
	s_setprio 0
	s_barrier
	s_add_i32 s42, s64, s69
	s_mov_b32 m0, s42
	s_nop 0
	global_load_lds_dwordx4 v140, s[48:49]
	s_add_i32 m0, s42, 0x2000
	s_add_u32 s42, s48, s90
	s_addc_u32 s43, s49, 0
	s_add_i32 s64, s65, s69
	global_load_lds_dwordx4 v144, s[48:49]
	s_mov_b32 m0, s64
	s_nop 0
	global_load_lds_dwordx4 v140, s[42:43]
	s_add_i32 m0, s64, 0x2000
	s_nop 0
	global_load_lds_dwordx4 v144, s[42:43]
	ds_read_b128 v[212:215], v160 offset:16384
	ds_read_b128 v[216:219], v160 offset:17408
	ds_read_b128 v[220:223], v160 offset:18432
	ds_read_b128 v[224:227], v160 offset:19456
	ds_read_b128 v[228:231], v160 offset:20480
	ds_read_b128 v[232:235], v160 offset:21504
	ds_read_b128 v[236:239], v160 offset:22528
	ds_read_b128 v[240:243], v160 offset:23552
	s_waitcnt vmcnt(6)
	s_waitcnt lgkmcnt(0)
	s_barrier
	s_setprio 1
	s_waitcnt lgkmcnt(0)
	v_mfma_f32_16x16x32_bf16 v[64:67], v[164:167], v[212:215], 0
	v_mfma_f32_16x16x32_bf16 v[60:63], v[188:191], v[212:215], 0
	v_mfma_f32_16x16x32_bf16 v[48:51], v[164:167], v[220:223], 0
	v_mfma_f32_16x16x32_bf16 v[44:47], v[188:191], v[220:223], 0
	v_mfma_f32_16x16x32_bf16 v[32:35], v[164:167], v[228:231], 0
	v_mfma_f32_16x16x32_bf16 v[28:31], v[188:191], v[228:231], 0
	v_mfma_f32_16x16x32_bf16 v[16:19], v[164:167], v[236:239], 0
	v_mfma_f32_16x16x32_bf16 v[12:15], v[188:191], v[236:239], 0
	v_mfma_f32_16x16x32_bf16 v[64:67], v[168:171], v[216:219], v[64:67]
	v_mfma_f32_16x16x32_bf16 v[60:63], v[192:195], v[216:219], v[60:63]
	v_mfma_f32_16x16x32_bf16 v[48:51], v[168:171], v[224:227], v[48:51]
	v_mfma_f32_16x16x32_bf16 v[44:47], v[192:195], v[224:227], v[44:47]
	v_mfma_f32_16x16x32_bf16 v[32:35], v[168:171], v[232:235], v[32:35]
	v_mfma_f32_16x16x32_bf16 v[28:31], v[192:195], v[232:235], v[28:31]
	v_mfma_f32_16x16x32_bf16 v[16:19], v[168:171], v[240:243], v[16:19]
	v_mfma_f32_16x16x32_bf16 v[12:15], v[192:195], v[240:243], v[12:15]
	s_setprio 0
	s_setprio 1
	v_mfma_f32_16x16x32_bf16 v[56:59], v[196:199], v[212:215], 0
	v_mfma_f32_16x16x32_bf16 v[52:55], v[204:207], v[212:215], 0
	v_mfma_f32_16x16x32_bf16 v[40:43], v[196:199], v[220:223], 0
	v_mfma_f32_16x16x32_bf16 v[36:39], v[204:207], v[220:223], 0
	v_mfma_f32_16x16x32_bf16 v[24:27], v[196:199], v[228:231], 0
	v_mfma_f32_16x16x32_bf16 v[20:23], v[204:207], v[228:231], 0
	v_mfma_f32_16x16x32_bf16 v[8:11], v[196:199], v[236:239], 0
	v_mfma_f32_16x16x32_bf16 v[4:7], v[204:207], v[236:239], 0
	v_mfma_f32_16x16x32_bf16 v[56:59], v[200:203], v[216:219], v[56:59]
	v_mfma_f32_16x16x32_bf16 v[52:55], v[208:211], v[216:219], v[52:55]
	v_mfma_f32_16x16x32_bf16 v[40:43], v[200:203], v[224:227], v[40:43]
	v_mfma_f32_16x16x32_bf16 v[36:39], v[208:211], v[224:227], v[36:39]
	v_mfma_f32_16x16x32_bf16 v[24:27], v[200:203], v[232:235], v[24:27]
	v_mfma_f32_16x16x32_bf16 v[20:23], v[208:211], v[232:235], v[20:23]
	v_mfma_f32_16x16x32_bf16 v[8:11], v[200:203], v[240:243], v[8:11]
	v_mfma_f32_16x16x32_bf16 v[4:7], v[208:211], v[240:243], v[4:7]
	s_setprio 0
	s_barrier
	s_add_i32 s64, 0, 0x18000
	v_add_u32_e32 v187, s64, v3
	s_add_i32 s65, 0, 0x1c000
	ds_read_b128 v[164:167], v187
	ds_read_b128 v[168:171], v187 offset:1024
	ds_read_b128 v[188:191], v187 offset:2048
	ds_read_b128 v[192:195], v187 offset:3072
	v_add_u32_e32 v187, s65, v3
	ds_read_b128 v[196:199], v187
	ds_read_b128 v[200:203], v187 offset:1024
	ds_read_b128 v[204:207], v187 offset:2048
	ds_read_b128 v[208:211], v187 offset:3072
	s_add_u32 s42, s50, s90
	s_addc_u32 s43, s51, 0
	s_mov_b32 m0, s56
	s_nop 0
	global_load_lds_dwordx4 v0, s[50:51]
	s_mov_b32 m0, s57
	s_nop 0
	global_load_lds_dwordx4 v142, s[50:51]
	s_mov_b32 m0, s58
	s_nop 0
	global_load_lds_dwordx4 v0, s[42:43]
	s_mov_b32 m0, s59
	s_nop 0
	global_load_lds_dwordx4 v142, s[42:43]
	ds_read_b128 v[212:215], v160 offset:32768
	ds_read_b128 v[216:219], v160 offset:33792
	ds_read_b128 v[220:223], v160 offset:34816
	ds_read_b128 v[224:227], v160 offset:35840
	ds_read_b128 v[228:231], v160 offset:36864
	ds_read_b128 v[232:235], v160 offset:37888
	ds_read_b128 v[236:239], v160 offset:38912
	ds_read_b128 v[240:243], v160 offset:39936
	s_waitcnt vmcnt(8)
	s_waitcnt lgkmcnt(8)
	s_barrier
	s_setprio 1
	s_waitcnt lgkmcnt(0)
	v_mfma_f32_16x16x32_bf16 v[128:131], v[164:167], v[212:215], v[128:131]
	v_mfma_f32_16x16x32_bf16 v[124:127], v[188:191], v[212:215], v[124:127]
	v_mfma_f32_16x16x32_bf16 v[112:115], v[164:167], v[220:223], v[112:115]
	v_mfma_f32_16x16x32_bf16 v[108:111], v[188:191], v[220:223], v[108:111]
	v_mfma_f32_16x16x32_bf16 v[96:99], v[164:167], v[228:231], v[96:99]
	v_mfma_f32_16x16x32_bf16 v[92:95], v[188:191], v[228:231], v[92:95]
	v_mfma_f32_16x16x32_bf16 v[80:83], v[164:167], v[236:239], v[80:83]
	v_mfma_f32_16x16x32_bf16 v[76:79], v[188:191], v[236:239], v[76:79]
	v_mfma_f32_16x16x32_bf16 v[128:131], v[168:171], v[216:219], v[128:131]
	v_mfma_f32_16x16x32_bf16 v[124:127], v[192:195], v[216:219], v[124:127]
	v_mfma_f32_16x16x32_bf16 v[112:115], v[168:171], v[224:227], v[112:115]
	v_mfma_f32_16x16x32_bf16 v[108:111], v[192:195], v[224:227], v[108:111]
	v_mfma_f32_16x16x32_bf16 v[96:99], v[168:171], v[232:235], v[96:99]
	v_mfma_f32_16x16x32_bf16 v[92:95], v[192:195], v[232:235], v[92:95]
	v_mfma_f32_16x16x32_bf16 v[80:83], v[168:171], v[240:243], v[80:83]
	v_mfma_f32_16x16x32_bf16 v[76:79], v[192:195], v[240:243], v[76:79]
	s_setprio 0
	s_setprio 1
	v_mfma_f32_16x16x32_bf16 v[120:123], v[196:199], v[212:215], v[120:123]
	v_mfma_f32_16x16x32_bf16 v[116:119], v[204:207], v[212:215], v[116:119]
	v_mfma_f32_16x16x32_bf16 v[104:107], v[196:199], v[220:223], v[104:107]
	v_mfma_f32_16x16x32_bf16 v[100:103], v[204:207], v[220:223], v[100:103]
	v_mfma_f32_16x16x32_bf16 v[88:91], v[196:199], v[228:231], v[88:91]
	v_mfma_f32_16x16x32_bf16 v[84:87], v[204:207], v[228:231], v[84:87]
	v_mfma_f32_16x16x32_bf16 v[72:75], v[196:199], v[236:239], v[72:75]
	v_mfma_f32_16x16x32_bf16 v[68:71], v[204:207], v[236:239], v[68:71]
	v_mfma_f32_16x16x32_bf16 v[120:123], v[200:203], v[216:219], v[120:123]
	v_mfma_f32_16x16x32_bf16 v[116:119], v[208:211], v[216:219], v[116:119]
	v_mfma_f32_16x16x32_bf16 v[104:107], v[200:203], v[224:227], v[104:107]
	v_mfma_f32_16x16x32_bf16 v[100:103], v[208:211], v[224:227], v[100:103]
	v_mfma_f32_16x16x32_bf16 v[88:91], v[200:203], v[232:235], v[88:91]
	v_mfma_f32_16x16x32_bf16 v[84:87], v[208:211], v[232:235], v[84:87]
	v_mfma_f32_16x16x32_bf16 v[72:75], v[200:203], v[240:243], v[72:75]
	v_mfma_f32_16x16x32_bf16 v[68:71], v[208:211], v[240:243], v[68:71]
	s_setprio 0
	s_barrier
	s_add_u32 s42, s48, 0x80
	s_addc_u32 s43, s49, 0
	s_add_i32 s50, s64, s69
	s_mov_b32 m0, s50
	s_nop 0
	global_load_lds_dwordx4 v140, s[42:43]
	s_add_i32 m0, s50, 0x2000
	s_nop 0
	global_load_lds_dwordx4 v144, s[42:43]
	s_add_u32 s42, s48, s53
	s_addc_u32 s43, s49, 0
	s_add_i32 s48, s65, s69
	s_mov_b32 m0, s48
	s_nop 0
	global_load_lds_dwordx4 v140, s[42:43]
	s_add_i32 m0, s48, 0x2000
	s_nop 0
	global_load_lds_dwordx4 v144, s[42:43]
	ds_read_b128 v[212:215], v160 offset:49152
	ds_read_b128 v[216:219], v160 offset:50176
	ds_read_b128 v[220:223], v160 offset:51200
	ds_read_b128 v[224:227], v160 offset:52224
	ds_read_b128 v[228:231], v160 offset:53248
	ds_read_b128 v[232:235], v160 offset:54272
	ds_read_b128 v[236:239], v160 offset:55296
	ds_read_b128 v[240:243], v160 offset:56320
	s_waitcnt vmcnt(6)
	s_waitcnt lgkmcnt(0)
	s_barrier
	s_setprio 1
	s_waitcnt lgkmcnt(0)
	v_mfma_f32_16x16x32_bf16 v[64:67], v[164:167], v[212:215], v[64:67]
	v_mfma_f32_16x16x32_bf16 v[60:63], v[188:191], v[212:215], v[60:63]
	v_mfma_f32_16x16x32_bf16 v[48:51], v[164:167], v[220:223], v[48:51]
	v_mfma_f32_16x16x32_bf16 v[44:47], v[188:191], v[220:223], v[44:47]
	v_mfma_f32_16x16x32_bf16 v[32:35], v[164:167], v[228:231], v[32:35]
	v_mfma_f32_16x16x32_bf16 v[28:31], v[188:191], v[228:231], v[28:31]
	v_mfma_f32_16x16x32_bf16 v[16:19], v[164:167], v[236:239], v[16:19]
	v_mfma_f32_16x16x32_bf16 v[12:15], v[188:191], v[236:239], v[12:15]
	v_mfma_f32_16x16x32_bf16 v[64:67], v[168:171], v[216:219], v[64:67]
	v_mfma_f32_16x16x32_bf16 v[60:63], v[192:195], v[216:219], v[60:63]
	v_mfma_f32_16x16x32_bf16 v[48:51], v[168:171], v[224:227], v[48:51]
	v_mfma_f32_16x16x32_bf16 v[44:47], v[192:195], v[224:227], v[44:47]
	v_mfma_f32_16x16x32_bf16 v[32:35], v[168:171], v[232:235], v[32:35]
	v_mfma_f32_16x16x32_bf16 v[28:31], v[192:195], v[232:235], v[28:31]
	v_mfma_f32_16x16x32_bf16 v[16:19], v[168:171], v[240:243], v[16:19]
	v_mfma_f32_16x16x32_bf16 v[12:15], v[192:195], v[240:243], v[12:15]
	s_setprio 0
	s_setprio 1
	v_mfma_f32_16x16x32_bf16 v[56:59], v[196:199], v[212:215], v[56:59]
	v_mfma_f32_16x16x32_bf16 v[52:55], v[204:207], v[212:215], v[52:55]
	v_mfma_f32_16x16x32_bf16 v[40:43], v[196:199], v[220:223], v[40:43]
	v_mfma_f32_16x16x32_bf16 v[36:39], v[204:207], v[220:223], v[36:39]
	v_mfma_f32_16x16x32_bf16 v[24:27], v[196:199], v[228:231], v[24:27]
	v_mfma_f32_16x16x32_bf16 v[20:23], v[204:207], v[228:231], v[20:23]
	v_mfma_f32_16x16x32_bf16 v[8:11], v[196:199], v[236:239], v[8:11]
	v_mfma_f32_16x16x32_bf16 v[4:7], v[204:207], v[236:239], v[4:7]
	v_mfma_f32_16x16x32_bf16 v[56:59], v[200:203], v[216:219], v[56:59]
	v_mfma_f32_16x16x32_bf16 v[52:55], v[208:211], v[216:219], v[52:55]
	v_mfma_f32_16x16x32_bf16 v[40:43], v[200:203], v[224:227], v[40:43]
	v_mfma_f32_16x16x32_bf16 v[36:39], v[208:211], v[224:227], v[36:39]
	v_mfma_f32_16x16x32_bf16 v[24:27], v[200:203], v[232:235], v[24:27]
	v_mfma_f32_16x16x32_bf16 v[20:23], v[208:211], v[232:235], v[20:23]
	v_mfma_f32_16x16x32_bf16 v[8:11], v[200:203], v[240:243], v[8:11]
	v_mfma_f32_16x16x32_bf16 v[4:7], v[208:211], v[240:243], v[4:7]
	s_setprio 0
	s_barrier
	s_add_i32 s63, s63, 2
	s_add_u32 s28, s28, 0x100
	s_addc_u32 s29, s29, 0
	s_cmp_gt_u32 s63, s55
	s_mov_b64 s[42:43], s[44:45]

.Lg1_loop:
	s_add_u32 s44, s42, 0x100
	s_addc_u32 s45, s43, 0
	s_cmp_eq_u32 s63, s54
	s_cselect_b32 s50, s26, s44
	s_cselect_b32 s51, s5, s45
	s_cselect_b32 s48, s27, s28
	s_cselect_b32 s49, s23, s29
	s_add_i32 s64, 0, 0x10000
	v_add_u32_e32 v187, s64, v3
	s_add_i32 s65, 0, 0x14000
	ds_read_b128 v[164:167], v187
	ds_read_b128 v[168:171], v187 offset:1024
	ds_read_b128 v[188:191], v187 offset:2048
	ds_read_b128 v[192:195], v187 offset:3072
	v_add_u32_e32 v187, s65, v3
	ds_read_b128 v[196:199], v187
	ds_read_b128 v[200:203], v187 offset:1024
	ds_read_b128 v[204:207], v187 offset:2048
	ds_read_b128 v[208:211], v187 offset:3072
	s_add_u32 s46, s42, 0x80
	s_addc_u32 s47, s43, 0
	s_add_u32 s42, s42, s53
	s_addc_u32 s43, s43, 0
	s_mov_b32 m0, s60
	s_nop 0
	global_load_lds_dwordx4 v0, s[46:47]
	s_mov_b32 m0, s61
	s_nop 0
	global_load_lds_dwordx4 v142, s[46:47]
	s_add_i32 m0, s56, 0xc000
	s_nop 0
	global_load_lds_dwordx4 v0, s[42:43]
	s_add_i32 m0, s56, 0xe000
	s_nop 0
	global_load_lds_dwordx4 v142, s[42:43]
	ds_read_b128 v[212:215], v160
	ds_read_b128 v[216:219], v160 offset:1024
	ds_read_b128 v[220:223], v160 offset:2048
	ds_read_b128 v[224:227], v160 offset:3072
	ds_read_b128 v[228:231], v160 offset:4096
	ds_read_b128 v[232:235], v160 offset:5120
	ds_read_b128 v[236:239], v160 offset:6144
	ds_read_b128 v[240:243], v160 offset:7168
	s_waitcnt vmcnt(8)
	s_waitcnt lgkmcnt(8)
	s_barrier
	s_setprio 1
	s_waitcnt lgkmcnt(0)
	v_mfma_f32_16x16x32_bf16 v[128:131], v[164:167], v[212:215], v[128:131]
	v_mfma_f32_16x16x32_bf16 v[124:127], v[188:191], v[212:215], v[124:127]
	v_mfma_f32_16x16x32_bf16 v[112:115], v[164:167], v[220:223], v[112:115]
	v_mfma_f32_16x16x32_bf16 v[108:111], v[188:191], v[220:223], v[108:111]
	v_mfma_f32_16x16x32_bf16 v[96:99], v[164:167], v[228:231], v[96:99]
	v_mfma_f32_16x16x32_bf16 v[92:95], v[188:191], v[228:231], v[92:95]
	v_mfma_f32_16x16x32_bf16 v[80:83], v[164:167], v[236:239], v[80:83]
	v_mfma_f32_16x16x32_bf16 v[76:79], v[188:191], v[236:239], v[76:79]
	v_mfma_f32_16x16x32_bf16 v[128:131], v[168:171], v[216:219], v[128:131]
	v_mfma_f32_16x16x32_bf16 v[124:127], v[192:195], v[216:219], v[124:127]
	v_mfma_f32_16x16x32_bf16 v[112:115], v[168:171], v[224:227], v[112:115]
	v_mfma_f32_16x16x32_bf16 v[108:111], v[192:195], v[224:227], v[108:111]
	v_mfma_f32_16x16x32_bf16 v[96:99], v[168:171], v[232:235], v[96:99]
	v_mfma_f32_16x16x32_bf16 v[92:95], v[192:195], v[232:235], v[92:95]
	v_mfma_f32_16x16x32_bf16 v[80:83], v[168:171], v[240:243], v[80:83]
	v_mfma_f32_16x16x32_bf16 v[76:79], v[192:195], v[240:243], v[76:79]
	s_setprio 0
	s_setprio 1
	v_mfma_f32_16x16x32_bf16 v[120:123], v[196:199], v[212:215], v[120:123]
	v_mfma_f32_16x16x32_bf16 v[116:119], v[204:207], v[212:215], v[116:119]
	v_mfma_f32_16x16x32_bf16 v[104:107], v[196:199], v[220:223], v[104:107]
	v_mfma_f32_16x16x32_bf16 v[100:103], v[204:207], v[220:223], v[100:103]
	v_mfma_f32_16x16x32_bf16 v[88:91], v[196:199], v[228:231], v[88:91]
	v_mfma_f32_16x16x32_bf16 v[84:87], v[204:207], v[228:231], v[84:87]
	v_mfma_f32_16x16x32_bf16 v[72:75], v[196:199], v[236:239], v[72:75]
	v_mfma_f32_16x16x32_bf16 v[68:71], v[204:207], v[236:239], v[68:71]
	v_mfma_f32_16x16x32_bf16 v[120:123], v[200:203], v[216:219], v[120:123]
	v_mfma_f32_16x16x32_bf16 v[116:119], v[208:211], v[216:219], v[116:119]
	v_mfma_f32_16x16x32_bf16 v[104:107], v[200:203], v[224:227], v[104:107]
	v_mfma_f32_16x16x32_bf16 v[100:103], v[208:211], v[224:227], v[100:103]
	v_mfma_f32_16x16x32_bf16 v[88:91], v[200:203], v[232:235], v[88:91]
	v_mfma_f32_16x16x32_bf16 v[84:87], v[208:211], v[232:235], v[84:87]
	v_mfma_f32_16x16x32_bf16 v[72:75], v[200:203], v[240:243], v[72:75]
	v_mfma_f32_16x16x32_bf16 v[68:71], v[208:211], v[240:243], v[68:71]
	s_setprio 0
	s_barrier
	s_add_i32 s42, s64, s69
	s_mov_b32 m0, s42
	s_nop 0
	global_load_lds_dwordx4 v140, s[48:49]
	s_add_i32 m0, s42, 0x2000
	s_add_u32 s42, s48, s90
	s_addc_u32 s43, s49, 0
	s_add_i32 s64, s65, s69
	global_load_lds_dwordx4 v144, s[48:49]
	s_mov_b32 m0, s64
	s_nop 0
	global_load_lds_dwordx4 v140, s[42:43]
	s_add_i32 m0, s64, 0x2000
	s_nop 0
	global_load_lds_dwordx4 v144, s[42:43]
	ds_read_b128 v[212:215], v160 offset:16384
	ds_read_b128 v[216:219], v160 offset:17408
	ds_read_b128 v[220:223], v160 offset:18432
	ds_read_b128 v[224:227], v160 offset:19456
	ds_read_b128 v[228:231], v160 offset:20480
	ds_read_b128 v[232:235], v160 offset:21504
	ds_read_b128 v[236:239], v160 offset:22528
	ds_read_b128 v[240:243], v160 offset:23552
	s_waitcnt vmcnt(6)
	s_waitcnt lgkmcnt(0)
	s_barrier
	s_setprio 1
	s_waitcnt lgkmcnt(0)
	v_mfma_f32_16x16x32_bf16 v[64:67], v[164:167], v[212:215], v[64:67]
	v_mfma_f32_16x16x32_bf16 v[60:63], v[188:191], v[212:215], v[60:63]
	v_mfma_f32_16x16x32_bf16 v[48:51], v[164:167], v[220:223], v[48:51]
	v_mfma_f32_16x16x32_bf16 v[44:47], v[188:191], v[220:223], v[44:47]
	v_mfma_f32_16x16x32_bf16 v[32:35], v[164:167], v[228:231], v[32:35]
	v_mfma_f32_16x16x32_bf16 v[28:31], v[188:191], v[228:231], v[28:31]
	v_mfma_f32_16x16x32_bf16 v[16:19], v[164:167], v[236:239], v[16:19]
	v_mfma_f32_16x16x32_bf16 v[12:15], v[188:191], v[236:239], v[12:15]
	v_mfma_f32_16x16x32_bf16 v[64:67], v[168:171], v[216:219], v[64:67]
	v_mfma_f32_16x16x32_bf16 v[60:63], v[192:195], v[216:219], v[60:63]
	v_mfma_f32_16x16x32_bf16 v[48:51], v[168:171], v[224:227], v[48:51]
	v_mfma_f32_16x16x32_bf16 v[44:47], v[192:195], v[224:227], v[44:47]
	v_mfma_f32_16x16x32_bf16 v[32:35], v[168:171], v[232:235], v[32:35]
	v_mfma_f32_16x16x32_bf16 v[28:31], v[192:195], v[232:235], v[28:31]
	v_mfma_f32_16x16x32_bf16 v[16:19], v[168:171], v[240:243], v[16:19]
	v_mfma_f32_16x16x32_bf16 v[12:15], v[192:195], v[240:243], v[12:15]
	s_setprio 0
	s_setprio 1
	v_mfma_f32_16x16x32_bf16 v[56:59], v[196:199], v[212:215], v[56:59]
	v_mfma_f32_16x16x32_bf16 v[52:55], v[204:207], v[212:215], v[52:55]
	v_mfma_f32_16x16x32_bf16 v[40:43], v[196:199], v[220:223], v[40:43]
	v_mfma_f32_16x16x32_bf16 v[36:39], v[204:207], v[220:223], v[36:39]
	v_mfma_f32_16x16x32_bf16 v[24:27], v[196:199], v[228:231], v[24:27]
	v_mfma_f32_16x16x32_bf16 v[20:23], v[204:207], v[228:231], v[20:23]
	v_mfma_f32_16x16x32_bf16 v[8:11], v[196:199], v[236:239], v[8:11]
	v_mfma_f32_16x16x32_bf16 v[4:7], v[204:207], v[236:239], v[4:7]
	v_mfma_f32_16x16x32_bf16 v[56:59], v[200:203], v[216:219], v[56:59]
	v_mfma_f32_16x16x32_bf16 v[52:55], v[208:211], v[216:219], v[52:55]
	v_mfma_f32_16x16x32_bf16 v[40:43], v[200:203], v[224:227], v[40:43]
	v_mfma_f32_16x16x32_bf16 v[36:39], v[208:211], v[224:227], v[36:39]
	v_mfma_f32_16x16x32_bf16 v[24:27], v[200:203], v[232:235], v[24:27]
	v_mfma_f32_16x16x32_bf16 v[20:23], v[208:211], v[232:235], v[20:23]
	v_mfma_f32_16x16x32_bf16 v[8:11], v[200:203], v[240:243], v[8:11]
	v_mfma_f32_16x16x32_bf16 v[4:7], v[208:211], v[240:243], v[4:7]
	s_setprio 0
	s_barrier
	s_add_i32 s64, 0, 0x18000
	v_add_u32_e32 v187, s64, v3
	s_add_i32 s65, 0, 0x1c000
	ds_read_b128 v[164:167], v187
	ds_read_b128 v[168:171], v187 offset:1024
	ds_read_b128 v[188:191], v187 offset:2048
	ds_read_b128 v[192:195], v187 offset:3072
	v_add_u32_e32 v187, s65, v3
	ds_read_b128 v[196:199], v187
	ds_read_b128 v[200:203], v187 offset:1024
	ds_read_b128 v[204:207], v187 offset:2048
	ds_read_b128 v[208:211], v187 offset:3072
	s_add_u32 s42, s50, s90
	s_addc_u32 s43, s51, 0
	s_mov_b32 m0, s56
	s_nop 0
	global_load_lds_dwordx4 v0, s[50:51]
	s_mov_b32 m0, s57
	s_nop 0
	global_load_lds_dwordx4 v142, s[50:51]
	s_mov_b32 m0, s58
	s_nop 0
	global_load_lds_dwordx4 v0, s[42:43]
	s_mov_b32 m0, s59
	s_nop 0
	global_load_lds_dwordx4 v142, s[42:43]
	ds_read_b128 v[212:215], v160 offset:32768
	ds_read_b128 v[216:219], v160 offset:33792
	ds_read_b128 v[220:223], v160 offset:34816
	ds_read_b128 v[224:227], v160 offset:35840
	ds_read_b128 v[228:231], v160 offset:36864
	ds_read_b128 v[232:235], v160 offset:37888
	ds_read_b128 v[236:239], v160 offset:38912
	ds_read_b128 v[240:243], v160 offset:39936
	s_waitcnt vmcnt(8)
	s_waitcnt lgkmcnt(8)
	s_barrier
	s_setprio 1
	s_waitcnt lgkmcnt(0)
	v_mfma_f32_16x16x32_bf16 v[128:131], v[164:167], v[212:215], v[128:131]
	v_mfma_f32_16x16x32_bf16 v[124:127], v[188:191], v[212:215], v[124:127]
	v_mfma_f32_16x16x32_bf16 v[112:115], v[164:167], v[220:223], v[112:115]
	v_mfma_f32_16x16x32_bf16 v[108:111], v[188:191], v[220:223], v[108:111]
	v_mfma_f32_16x16x32_bf16 v[96:99], v[164:167], v[228:231], v[96:99]
	v_mfma_f32_16x16x32_bf16 v[92:95], v[188:191], v[228:231], v[92:95]
	v_mfma_f32_16x16x32_bf16 v[80:83], v[164:167], v[236:239], v[80:83]
	v_mfma_f32_16x16x32_bf16 v[76:79], v[188:191], v[236:239], v[76:79]
	v_mfma_f32_16x16x32_bf16 v[128:131], v[168:171], v[216:219], v[128:131]
	v_mfma_f32_16x16x32_bf16 v[124:127], v[192:195], v[216:219], v[124:127]
	v_mfma_f32_16x16x32_bf16 v[112:115], v[168:171], v[224:227], v[112:115]
	v_mfma_f32_16x16x32_bf16 v[108:111], v[192:195], v[224:227], v[108:111]
	v_mfma_f32_16x16x32_bf16 v[96:99], v[168:171], v[232:235], v[96:99]
	v_mfma_f32_16x16x32_bf16 v[92:95], v[192:195], v[232:235], v[92:95]
	v_mfma_f32_16x16x32_bf16 v[80:83], v[168:171], v[240:243], v[80:83]
	v_mfma_f32_16x16x32_bf16 v[76:79], v[192:195], v[240:243], v[76:79]
	s_setprio 0
	s_setprio 1
	v_mfma_f32_16x16x32_bf16 v[120:123], v[196:199], v[212:215], v[120:123]
	v_mfma_f32_16x16x32_bf16 v[116:119], v[204:207], v[212:215], v[116:119]
	v_mfma_f32_16x16x32_bf16 v[104:107], v[196:199], v[220:223], v[104:107]
	v_mfma_f32_16x16x32_bf16 v[100:103], v[204:207], v[220:223], v[100:103]
	v_mfma_f32_16x16x32_bf16 v[88:91], v[196:199], v[228:231], v[88:91]
	v_mfma_f32_16x16x32_bf16 v[84:87], v[204:207], v[228:231], v[84:87]
	v_mfma_f32_16x16x32_bf16 v[72:75], v[196:199], v[236:239], v[72:75]
	v_mfma_f32_16x16x32_bf16 v[68:71], v[204:207], v[236:239], v[68:71]
	v_mfma_f32_16x16x32_bf16 v[120:123], v[200:203], v[216:219], v[120:123]
	v_mfma_f32_16x16x32_bf16 v[116:119], v[208:211], v[216:219], v[116:119]
	v_mfma_f32_16x16x32_bf16 v[104:107], v[200:203], v[224:227], v[104:107]
	v_mfma_f32_16x16x32_bf16 v[100:103], v[208:211], v[224:227], v[100:103]
	v_mfma_f32_16x16x32_bf16 v[88:91], v[200:203], v[232:235], v[88:91]
	v_mfma_f32_16x16x32_bf16 v[84:87], v[208:211], v[232:235], v[84:87]
	v_mfma_f32_16x16x32_bf16 v[72:75], v[200:203], v[240:243], v[72:75]
	v_mfma_f32_16x16x32_bf16 v[68:71], v[208:211], v[240:243], v[68:71]
	s_setprio 0
	s_barrier
	s_add_u32 s42, s48, 0x80
	s_addc_u32 s43, s49, 0
	s_add_i32 s50, s64, s69
	s_mov_b32 m0, s50
	s_nop 0
	global_load_lds_dwordx4 v140, s[42:43]
	s_add_i32 m0, s50, 0x2000
	s_nop 0
	global_load_lds_dwordx4 v144, s[42:43]
	s_add_u32 s42, s48, s53
	s_addc_u32 s43, s49, 0
	s_add_i32 s48, s65, s69
	s_mov_b32 m0, s48
	s_nop 0
	global_load_lds_dwordx4 v140, s[42:43]
	s_add_i32 m0, s48, 0x2000
	s_nop 0
	global_load_lds_dwordx4 v144, s[42:43]
	ds_read_b128 v[212:215], v160 offset:49152
	ds_read_b128 v[216:219], v160 offset:50176
	ds_read_b128 v[220:223], v160 offset:51200
	ds_read_b128 v[224:227], v160 offset:52224
	ds_read_b128 v[228:231], v160 offset:53248
	ds_read_b128 v[232:235], v160 offset:54272
	ds_read_b128 v[236:239], v160 offset:55296
	ds_read_b128 v[240:243], v160 offset:56320
	s_waitcnt vmcnt(6)
	s_waitcnt lgkmcnt(0)
	s_barrier
	s_setprio 1
	s_waitcnt lgkmcnt(0)
	v_mfma_f32_16x16x32_bf16 v[64:67], v[164:167], v[212:215], v[64:67]
	v_mfma_f32_16x16x32_bf16 v[60:63], v[188:191], v[212:215], v[60:63]
	v_mfma_f32_16x16x32_bf16 v[48:51], v[164:167], v[220:223], v[48:51]
	v_mfma_f32_16x16x32_bf16 v[44:47], v[188:191], v[220:223], v[44:47]
	v_mfma_f32_16x16x32_bf16 v[32:35], v[164:167], v[228:231], v[32:35]
	v_mfma_f32_16x16x32_bf16 v[28:31], v[188:191], v[228:231], v[28:31]
	v_mfma_f32_16x16x32_bf16 v[16:19], v[164:167], v[236:239], v[16:19]
	v_mfma_f32_16x16x32_bf16 v[12:15], v[188:191], v[236:239], v[12:15]
	v_mfma_f32_16x16x32_bf16 v[64:67], v[168:171], v[216:219], v[64:67]
	v_mfma_f32_16x16x32_bf16 v[60:63], v[192:195], v[216:219], v[60:63]
	v_mfma_f32_16x16x32_bf16 v[48:51], v[168:171], v[224:227], v[48:51]
	v_mfma_f32_16x16x32_bf16 v[44:47], v[192:195], v[224:227], v[44:47]
	v_mfma_f32_16x16x32_bf16 v[32:35], v[168:171], v[232:235], v[32:35]
	v_mfma_f32_16x16x32_bf16 v[28:31], v[192:195], v[232:235], v[28:31]
	v_mfma_f32_16x16x32_bf16 v[16:19], v[168:171], v[240:243], v[16:19]
	v_mfma_f32_16x16x32_bf16 v[12:15], v[192:195], v[240:243], v[12:15]
	s_setprio 0
	s_setprio 1
	v_mfma_f32_16x16x32_bf16 v[56:59], v[196:199], v[212:215], v[56:59]
	v_mfma_f32_16x16x32_bf16 v[52:55], v[204:207], v[212:215], v[52:55]
	v_mfma_f32_16x16x32_bf16 v[40:43], v[196:199], v[220:223], v[40:43]
	v_mfma_f32_16x16x32_bf16 v[36:39], v[204:207], v[220:223], v[36:39]
	v_mfma_f32_16x16x32_bf16 v[24:27], v[196:199], v[228:231], v[24:27]
	v_mfma_f32_16x16x32_bf16 v[20:23], v[204:207], v[228:231], v[20:23]
	v_mfma_f32_16x16x32_bf16 v[8:11], v[196:199], v[236:239], v[8:11]
	v_mfma_f32_16x16x32_bf16 v[4:7], v[204:207], v[236:239], v[4:7]
	v_mfma_f32_16x16x32_bf16 v[56:59], v[200:203], v[216:219], v[56:59]
	v_mfma_f32_16x16x32_bf16 v[52:55], v[208:211], v[216:219], v[52:55]
	v_mfma_f32_16x16x32_bf16 v[40:43], v[200:203], v[224:227], v[40:43]
	v_mfma_f32_16x16x32_bf16 v[36:39], v[208:211], v[224:227], v[36:39]
	v_mfma_f32_16x16x32_bf16 v[24:27], v[200:203], v[232:235], v[24:27]
	v_mfma_f32_16x16x32_bf16 v[20:23], v[208:211], v[232:235], v[20:23]
	v_mfma_f32_16x16x32_bf16 v[8:11], v[200:203], v[240:243], v[8:11]
	v_mfma_f32_16x16x32_bf16 v[4:7], v[208:211], v[240:243], v[4:7]
	s_setprio 0
	s_barrier
	s_add_i32 s63, s63, 2
	s_add_u32 s28, s28, 0x100
	s_addc_u32 s29, s29, 0
	s_cmp_gt_u32 s63, s55
	s_mov_b64 s[42:43], s[44:45]
	s_cbranch_scc0 .Lg1_loop
	v_readlane_b32 s5, v250, 0
	v_readlane_b32 s23, v250, 1
	v_readlane_b32 s26, v250, 2
	v_readlane_b32 s27, v250, 3
	v_readlane_b32 s28, v250, 4
	v_readlane_b32 s29, v250, 5
	v_readlane_b32 s42, v250, 6
	v_readlane_b32 s43, v250, 7
	v_readlane_b32 s44, v250, 8
	v_readlane_b32 s45, v250, 9
	v_readlane_b32 s46, v250, 10
	v_readlane_b32 s47, v250, 11
	v_readlane_b32 s48, v250, 12
	v_readlane_b32 s49, v250, 13
	v_readlane_b32 s50, v250, 14
	v_readlane_b32 s51, v250, 15
	v_readlane_b32 s53, v250, 16
	v_readlane_b32 s54, v250, 17
	v_readlane_b32 s55, v250, 18
	v_readlane_b32 s56, v250, 19
	v_readlane_b32 s57, v250, 20
	v_readlane_b32 s58, v250, 21
	v_readlane_b32 s59, v250, 22
	v_readlane_b32 s60, v250, 23
	v_readlane_b32 s61, v250, 24
	v_readlane_b32 s63, v250, 25
	v_readlane_b32 s64, v250, 26
	v_readlane_b32 s65, v250, 27
	s_and_b64 vcc, exec, s[14:15]
	s_cbranch_vccz .LBB0_419
	s_barrier

.LBB0_499:
	s_ashr_i32 s5, s4, 31
	s_lshl_b64 s[24:25], s[4:5], 19
	s_add_u32 s24, s52, s24
	s_addc_u32 s25, s53, s25
	s_and_b64 s[26:27], s[40:41], exec
	s_cselect_b32 s5, s25, s43
	s_cselect_b32 s26, s24, s42
	s_ashr_i32 s23, s22, 31
	s_lshl_b64 s[28:29], s[22:23], 19
	s_add_u32 s36, s54, s28
	s_addc_u32 s37, s55, s29
	s_and_b64 s[28:29], s[40:41], exec
	s_cselect_b32 s23, s37, s45
	s_cselect_b32 s27, s36, s44
	s_add_u32 s28, s44, 0x100
	v_mov_b32_e32 v4, 0
	s_addc_u32 s29, s45, 0
	s_mov_b32 s63, -2
	s_add_u32 s44, s42, 0x100
	s_addc_u32 s45, s43, 0
	s_cmp_eq_u32 s63, 12
	s_cselect_b32 s50, s26, s44
	s_cselect_b32 s51, s5, s45
	s_cselect_b32 s48, s27, s28
	s_cselect_b32 s49, s23, s29
	s_add_i32 s64, 0, 0x10000
	v_add_u32_e32 v138, s64, v3
	s_add_i32 s65, 0, 0x14000
	ds_read_b128 v[146:149], v138
	ds_read_b128 v[150:153], v138 offset:1024
	ds_read_b128 v[154:157], v138 offset:2048
	ds_read_b128 v[158:161], v138 offset:3072
	v_add_u32_e32 v138, s65, v3
	ds_read_b128 v[162:165], v138
	ds_read_b128 v[166:169], v138 offset:1024
	ds_read_b128 v[170:173], v138 offset:2048
	ds_read_b128 v[186:189], v138 offset:3072
	s_add_u32 s46, s42, 0x80
	s_addc_u32 s47, s43, 0
	s_add_u32 s42, s42, 0x40080
	s_addc_u32 s43, s43, 0
	s_mov_b32 m0, s60
	s_nop 0
	global_load_lds_dwordx4 v144, s[46:47]
	s_mov_b32 m0, s61
	s_nop 0
	global_load_lds_dwordx4 v140, s[46:47]
	s_add_i32 m0, s56, 0xc000
	s_nop 0
	global_load_lds_dwordx4 v144, s[42:43]
	s_add_i32 m0, s56, 0xe000
	s_nop 0
	global_load_lds_dwordx4 v140, s[42:43]
	ds_read_b128 v[190:193], v132
	ds_read_b128 v[194:197], v132 offset:1024
	ds_read_b128 v[198:201], v132 offset:2048
	ds_read_b128 v[202:205], v132 offset:3072
	ds_read_b128 v[206:209], v132 offset:4096
	ds_read_b128 v[210:213], v132 offset:5120
	ds_read_b128 v[214:217], v132 offset:6144
	ds_read_b128 v[218:221], v132 offset:7168
	s_waitcnt vmcnt(8)
	s_waitcnt lgkmcnt(8)
	s_barrier
	s_setprio 1
	s_waitcnt lgkmcnt(0)
	v_mfma_f32_16x16x32_bf16 v[128:131], v[146:149], v[190:193], 0
	v_mfma_f32_16x16x32_bf16 v[124:127], v[154:157], v[190:193], 0
	v_mfma_f32_16x16x32_bf16 v[112:115], v[146:149], v[198:201], 0
	v_mfma_f32_16x16x32_bf16 v[108:111], v[154:157], v[198:201], 0
	v_mfma_f32_16x16x32_bf16 v[96:99], v[146:149], v[206:209], 0
	v_mfma_f32_16x16x32_bf16 v[92:95], v[154:157], v[206:209], 0
	v_mfma_f32_16x16x32_bf16 v[80:83], v[146:149], v[214:217], 0
	v_mfma_f32_16x16x32_bf16 v[76:79], v[154:157], v[214:217], 0
	v_mfma_f32_16x16x32_bf16 v[128:131], v[150:153], v[194:197], v[128:131]
	v_mfma_f32_16x16x32_bf16 v[124:127], v[158:161], v[194:197], v[124:127]
	v_mfma_f32_16x16x32_bf16 v[112:115], v[150:153], v[202:205], v[112:115]
	v_mfma_f32_16x16x32_bf16 v[108:111], v[158:161], v[202:205], v[108:111]
	v_mfma_f32_16x16x32_bf16 v[96:99], v[150:153], v[210:213], v[96:99]
	v_mfma_f32_16x16x32_bf16 v[92:95], v[158:161], v[210:213], v[92:95]
	v_mfma_f32_16x16x32_bf16 v[80:83], v[150:153], v[218:221], v[80:83]
	v_mfma_f32_16x16x32_bf16 v[76:79], v[158:161], v[218:221], v[76:79]
	s_setprio 0
	s_setprio 1
	v_mfma_f32_16x16x32_bf16 v[120:123], v[162:165], v[190:193], 0
	v_mfma_f32_16x16x32_bf16 v[116:119], v[170:173], v[190:193], 0
	v_mfma_f32_16x16x32_bf16 v[104:107], v[162:165], v[198:201], 0
	v_mfma_f32_16x16x32_bf16 v[100:103], v[170:173], v[198:201], 0
	v_mfma_f32_16x16x32_bf16 v[88:91], v[162:165], v[206:209], 0
	v_mfma_f32_16x16x32_bf16 v[84:87], v[170:173], v[206:209], 0
	v_mfma_f32_16x16x32_bf16 v[72:75], v[162:165], v[214:217], 0
	v_mfma_f32_16x16x32_bf16 v[68:71], v[170:173], v[214:217], 0
	v_mfma_f32_16x16x32_bf16 v[120:123], v[166:169], v[194:197], v[120:123]
	v_mfma_f32_16x16x32_bf16 v[116:119], v[186:189], v[194:197], v[116:119]
	v_mfma_f32_16x16x32_bf16 v[104:107], v[166:169], v[202:205], v[104:107]
	v_mfma_f32_16x16x32_bf16 v[100:103], v[186:189], v[202:205], v[100:103]
	v_mfma_f32_16x16x32_bf16 v[88:91], v[166:169], v[210:213], v[88:91]
	v_mfma_f32_16x16x32_bf16 v[84:87], v[186:189], v[210:213], v[84:87]
	v_mfma_f32_16x16x32_bf16 v[72:75], v[166:169], v[218:221], v[72:75]
	v_mfma_f32_16x16x32_bf16 v[68:71], v[186:189], v[218:221], v[68:71]
	s_setprio 0
	s_barrier
	s_add_i32 s42, s64, s69
	s_mov_b32 m0, s42
	s_nop 0
	global_load_lds_dwordx4 v142, s[48:49]
	s_add_i32 m0, s42, 0x2000
	s_add_u32 s42, s48, 0x40000
	s_addc_u32 s43, s49, 0
	s_add_i32 s64, s65, s69
	global_load_lds_dwordx4 v0, s[48:49]
	s_mov_b32 m0, s64
	s_nop 0
	global_load_lds_dwordx4 v142, s[42:43]
	s_add_i32 m0, s64, 0x2000
	s_nop 0
	global_load_lds_dwordx4 v0, s[42:43]
	ds_read_b128 v[190:193], v132 offset:16384
	ds_read_b128 v[194:197], v132 offset:17408
	ds_read_b128 v[198:201], v132 offset:18432
	ds_read_b128 v[202:205], v132 offset:19456
	ds_read_b128 v[206:209], v132 offset:20480
	ds_read_b128 v[210:213], v132 offset:21504
	ds_read_b128 v[214:217], v132 offset:22528
	ds_read_b128 v[218:221], v132 offset:23552
	s_waitcnt vmcnt(6)
	s_waitcnt lgkmcnt(0)
	s_barrier
	s_setprio 1
	s_waitcnt lgkmcnt(0)
	v_mfma_f32_16x16x32_bf16 v[64:67], v[146:149], v[190:193], 0
	v_mfma_f32_16x16x32_bf16 v[60:63], v[154:157], v[190:193], 0
	v_mfma_f32_16x16x32_bf16 v[48:51], v[146:149], v[198:201], 0
	v_mfma_f32_16x16x32_bf16 v[44:47], v[154:157], v[198:201], 0
	v_mfma_f32_16x16x32_bf16 v[32:35], v[146:149], v[206:209], 0
	v_mfma_f32_16x16x32_bf16 v[28:31], v[154:157], v[206:209], 0
	v_mfma_f32_16x16x32_bf16 v[16:19], v[146:149], v[214:217], 0
	v_mfma_f32_16x16x32_bf16 v[12:15], v[154:157], v[214:217], 0
	v_mfma_f32_16x16x32_bf16 v[64:67], v[150:153], v[194:197], v[64:67]
	v_mfma_f32_16x16x32_bf16 v[60:63], v[158:161], v[194:197], v[60:63]
	v_mfma_f32_16x16x32_bf16 v[48:51], v[150:153], v[202:205], v[48:51]
	v_mfma_f32_16x16x32_bf16 v[44:47], v[158:161], v[202:205], v[44:47]
	v_mfma_f32_16x16x32_bf16 v[32:35], v[150:153], v[210:213], v[32:35]
	v_mfma_f32_16x16x32_bf16 v[28:31], v[158:161], v[210:213], v[28:31]
	v_mfma_f32_16x16x32_bf16 v[16:19], v[150:153], v[218:221], v[16:19]
	v_mfma_f32_16x16x32_bf16 v[12:15], v[158:161], v[218:221], v[12:15]
	s_setprio 0
	s_setprio 1
	v_mfma_f32_16x16x32_bf16 v[56:59], v[162:165], v[190:193], 0
	v_mfma_f32_16x16x32_bf16 v[52:55], v[170:173], v[190:193], 0
	v_mfma_f32_16x16x32_bf16 v[40:43], v[162:165], v[198:201], 0
	v_mfma_f32_16x16x32_bf16 v[36:39], v[170:173], v[198:201], 0
	v_mfma_f32_16x16x32_bf16 v[24:27], v[162:165], v[206:209], 0
	v_mfma_f32_16x16x32_bf16 v[20:23], v[170:173], v[206:209], 0
	v_mfma_f32_16x16x32_bf16 v[8:11], v[162:165], v[214:217], 0
	v_mfma_f32_16x16x32_bf16 v[4:7], v[170:173], v[214:217], 0
	v_mfma_f32_16x16x32_bf16 v[56:59], v[166:169], v[194:197], v[56:59]
	v_mfma_f32_16x16x32_bf16 v[52:55], v[186:189], v[194:197], v[52:55]
	v_mfma_f32_16x16x32_bf16 v[40:43], v[166:169], v[202:205], v[40:43]
	v_mfma_f32_16x16x32_bf16 v[36:39], v[186:189], v[202:205], v[36:39]
	v_mfma_f32_16x16x32_bf16 v[24:27], v[166:169], v[210:213], v[24:27]
	v_mfma_f32_16x16x32_bf16 v[20:23], v[186:189], v[210:213], v[20:23]
	v_mfma_f32_16x16x32_bf16 v[8:11], v[166:169], v[218:221], v[8:11]
	v_mfma_f32_16x16x32_bf16 v[4:7], v[186:189], v[218:221], v[4:7]
	s_setprio 0
	s_barrier
	s_add_i32 s64, 0, 0x18000
	v_add_u32_e32 v138, s64, v3
	s_add_i32 s65, 0, 0x1c000
	ds_read_b128 v[146:149], v138
	ds_read_b128 v[150:153], v138 offset:1024
	ds_read_b128 v[154:157], v138 offset:2048
	ds_read_b128 v[158:161], v138 offset:3072
	v_add_u32_e32 v138, s65, v3
	ds_read_b128 v[162:165], v138
	ds_read_b128 v[166:169], v138 offset:1024
	ds_read_b128 v[170:173], v138 offset:2048
	ds_read_b128 v[186:189], v138 offset:3072
	s_add_u32 s42, s50, 0x40000
	s_addc_u32 s43, s51, 0
	s_mov_b32 m0, s56
	s_nop 0
	global_load_lds_dwordx4 v144, s[50:51]
	s_mov_b32 m0, s57
	s_nop 0
	global_load_lds_dwordx4 v140, s[50:51]
	s_mov_b32 m0, s58
	s_nop 0
	global_load_lds_dwordx4 v144, s[42:43]
	s_mov_b32 m0, s59
	s_nop 0
	global_load_lds_dwordx4 v140, s[42:43]
	ds_read_b128 v[190:193], v132 offset:32768
	ds_read_b128 v[194:197], v132 offset:33792
	ds_read_b128 v[198:201], v132 offset:34816
	ds_read_b128 v[202:205], v132 offset:35840
	ds_read_b128 v[206:209], v132 offset:36864
	ds_read_b128 v[210:213], v132 offset:37888
	ds_read_b128 v[214:217], v132 offset:38912
	ds_read_b128 v[218:221], v132 offset:39936
	s_waitcnt vmcnt(8)
	s_waitcnt lgkmcnt(8)
	s_barrier
	s_setprio 1
	s_waitcnt lgkmcnt(0)
	v_mfma_f32_16x16x32_bf16 v[128:131], v[146:149], v[190:193], v[128:131]
	v_mfma_f32_16x16x32_bf16 v[124:127], v[154:157], v[190:193], v[124:127]
	v_mfma_f32_16x16x32_bf16 v[112:115], v[146:149], v[198:201], v[112:115]
	v_mfma_f32_16x16x32_bf16 v[108:111], v[154:157], v[198:201], v[108:111]
	v_mfma_f32_16x16x32_bf16 v[96:99], v[146:149], v[206:209], v[96:99]
	v_mfma_f32_16x16x32_bf16 v[92:95], v[154:157], v[206:209], v[92:95]
	v_mfma_f32_16x16x32_bf16 v[80:83], v[146:149], v[214:217], v[80:83]
	v_mfma_f32_16x16x32_bf16 v[76:79], v[154:157], v[214:217], v[76:79]
	v_mfma_f32_16x16x32_bf16 v[128:131], v[150:153], v[194:197], v[128:131]
	v_mfma_f32_16x16x32_bf16 v[124:127], v[158:161], v[194:197], v[124:127]
	v_mfma_f32_16x16x32_bf16 v[112:115], v[150:153], v[202:205], v[112:115]
	v_mfma_f32_16x16x32_bf16 v[108:111], v[158:161], v[202:205], v[108:111]
	v_mfma_f32_16x16x32_bf16 v[96:99], v[150:153], v[210:213], v[96:99]
	v_mfma_f32_16x16x32_bf16 v[92:95], v[158:161], v[210:213], v[92:95]
	v_mfma_f32_16x16x32_bf16 v[80:83], v[150:153], v[218:221], v[80:83]
	v_mfma_f32_16x16x32_bf16 v[76:79], v[158:161], v[218:221], v[76:79]
	s_setprio 0
	s_setprio 1
	v_mfma_f32_16x16x32_bf16 v[120:123], v[162:165], v[190:193], v[120:123]
	v_mfma_f32_16x16x32_bf16 v[116:119], v[170:173], v[190:193], v[116:119]
	v_mfma_f32_16x16x32_bf16 v[104:107], v[162:165], v[198:201], v[104:107]
	v_mfma_f32_16x16x32_bf16 v[100:103], v[170:173], v[198:201], v[100:103]
	v_mfma_f32_16x16x32_bf16 v[88:91], v[162:165], v[206:209], v[88:91]
	v_mfma_f32_16x16x32_bf16 v[84:87], v[170:173], v[206:209], v[84:87]
	v_mfma_f32_16x16x32_bf16 v[72:75], v[162:165], v[214:217], v[72:75]
	v_mfma_f32_16x16x32_bf16 v[68:71], v[170:173], v[214:217], v[68:71]
	v_mfma_f32_16x16x32_bf16 v[120:123], v[166:169], v[194:197], v[120:123]
	v_mfma_f32_16x16x32_bf16 v[116:119], v[186:189], v[194:197], v[116:119]
	v_mfma_f32_16x16x32_bf16 v[104:107], v[166:169], v[202:205], v[104:107]
	v_mfma_f32_16x16x32_bf16 v[100:103], v[186:189], v[202:205], v[100:103]
	v_mfma_f32_16x16x32_bf16 v[88:91], v[166:169], v[210:213], v[88:91]
	v_mfma_f32_16x16x32_bf16 v[84:87], v[186:189], v[210:213], v[84:87]
	v_mfma_f32_16x16x32_bf16 v[72:75], v[166:169], v[218:221], v[72:75]
	v_mfma_f32_16x16x32_bf16 v[68:71], v[186:189], v[218:221], v[68:71]
	s_setprio 0
	s_barrier
	s_add_u32 s42, s48, 0x80
	s_addc_u32 s43, s49, 0
	s_add_i32 s50, s64, s69
	s_mov_b32 m0, s50
	s_nop 0
	global_load_lds_dwordx4 v142, s[42:43]
	s_add_i32 m0, s50, 0x2000
	s_nop 0
	global_load_lds_dwordx4 v0, s[42:43]
	s_add_u32 s42, s48, 0x40080
	s_addc_u32 s43, s49, 0
	s_add_i32 s48, s65, s69
	s_mov_b32 m0, s48
	s_nop 0
	global_load_lds_dwordx4 v142, s[42:43]
	s_add_i32 m0, s48, 0x2000
	s_nop 0
	global_load_lds_dwordx4 v0, s[42:43]
	ds_read_b128 v[190:193], v132 offset:49152
	ds_read_b128 v[194:197], v132 offset:50176
	ds_read_b128 v[198:201], v132 offset:51200
	ds_read_b128 v[202:205], v132 offset:52224
	ds_read_b128 v[206:209], v132 offset:53248
	ds_read_b128 v[210:213], v132 offset:54272
	ds_read_b128 v[214:217], v132 offset:55296
	ds_read_b128 v[218:221], v132 offset:56320
	s_waitcnt vmcnt(6)
	s_waitcnt lgkmcnt(0)
	s_barrier
	s_setprio 1
	s_waitcnt lgkmcnt(0)
	v_mfma_f32_16x16x32_bf16 v[64:67], v[146:149], v[190:193], v[64:67]
	v_mfma_f32_16x16x32_bf16 v[60:63], v[154:157], v[190:193], v[60:63]
	v_mfma_f32_16x16x32_bf16 v[48:51], v[146:149], v[198:201], v[48:51]
	v_mfma_f32_16x16x32_bf16 v[44:47], v[154:157], v[198:201], v[44:47]
	v_mfma_f32_16x16x32_bf16 v[32:35], v[146:149], v[206:209], v[32:35]
	v_mfma_f32_16x16x32_bf16 v[28:31], v[154:157], v[206:209], v[28:31]
	v_mfma_f32_16x16x32_bf16 v[16:19], v[146:149], v[214:217], v[16:19]
	v_mfma_f32_16x16x32_bf16 v[12:15], v[154:157], v[214:217], v[12:15]
	v_mfma_f32_16x16x32_bf16 v[64:67], v[150:153], v[194:197], v[64:67]
	v_mfma_f32_16x16x32_bf16 v[60:63], v[158:161], v[194:197], v[60:63]
	v_mfma_f32_16x16x32_bf16 v[48:51], v[150:153], v[202:205], v[48:51]
	v_mfma_f32_16x16x32_bf16 v[44:47], v[158:161], v[202:205], v[44:47]
	v_mfma_f32_16x16x32_bf16 v[32:35], v[150:153], v[210:213], v[32:35]
	v_mfma_f32_16x16x32_bf16 v[28:31], v[158:161], v[210:213], v[28:31]
	v_mfma_f32_16x16x32_bf16 v[16:19], v[150:153], v[218:221], v[16:19]
	v_mfma_f32_16x16x32_bf16 v[12:15], v[158:161], v[218:221], v[12:15]
	s_setprio 0
	s_setprio 1
	v_mfma_f32_16x16x32_bf16 v[56:59], v[162:165], v[190:193], v[56:59]
	v_mfma_f32_16x16x32_bf16 v[52:55], v[170:173], v[190:193], v[52:55]
	v_mfma_f32_16x16x32_bf16 v[40:43], v[162:165], v[198:201], v[40:43]
	v_mfma_f32_16x16x32_bf16 v[36:39], v[170:173], v[198:201], v[36:39]
	v_mfma_f32_16x16x32_bf16 v[24:27], v[162:165], v[206:209], v[24:27]
	v_mfma_f32_16x16x32_bf16 v[20:23], v[170:173], v[206:209], v[20:23]
	v_mfma_f32_16x16x32_bf16 v[8:11], v[162:165], v[214:217], v[8:11]
	v_mfma_f32_16x16x32_bf16 v[4:7], v[170:173], v[214:217], v[4:7]
	v_mfma_f32_16x16x32_bf16 v[56:59], v[166:169], v[194:197], v[56:59]
	v_mfma_f32_16x16x32_bf16 v[52:55], v[186:189], v[194:197], v[52:55]
	v_mfma_f32_16x16x32_bf16 v[40:43], v[166:169], v[202:205], v[40:43]
	v_mfma_f32_16x16x32_bf16 v[36:39], v[186:189], v[202:205], v[36:39]
	v_mfma_f32_16x16x32_bf16 v[24:27], v[166:169], v[210:213], v[24:27]
	v_mfma_f32_16x16x32_bf16 v[20:23], v[186:189], v[210:213], v[20:23]
	v_mfma_f32_16x16x32_bf16 v[8:11], v[166:169], v[218:221], v[8:11]
	v_mfma_f32_16x16x32_bf16 v[4:7], v[186:189], v[218:221], v[4:7]
	s_setprio 0
	s_barrier
	s_add_i32 s63, s63, 2
	s_add_u32 s28, s28, 0x100
	s_addc_u32 s29, s29, 0
	s_cmp_gt_u32 s63, 13
	s_mov_b64 s[42:43], s[44:45]

.LBB0_500:
	s_add_u32 s44, s42, 0x100
	s_addc_u32 s45, s43, 0
	s_cmp_eq_u32 s63, 12
	s_cselect_b32 s50, s26, s44
	s_cselect_b32 s51, s5, s45
	s_cselect_b32 s48, s27, s28
	s_cselect_b32 s49, s23, s29
	s_add_i32 s64, 0, 0x10000
	v_add_u32_e32 v138, s64, v3
	s_add_i32 s65, 0, 0x14000
	ds_read_b128 v[146:149], v138
	ds_read_b128 v[150:153], v138 offset:1024
	ds_read_b128 v[154:157], v138 offset:2048
	ds_read_b128 v[158:161], v138 offset:3072
	v_add_u32_e32 v138, s65, v3
	ds_read_b128 v[162:165], v138
	ds_read_b128 v[166:169], v138 offset:1024
	ds_read_b128 v[170:173], v138 offset:2048
	ds_read_b128 v[186:189], v138 offset:3072
	s_add_u32 s46, s42, 0x80
	s_addc_u32 s47, s43, 0
	s_add_u32 s42, s42, 0x40080
	s_addc_u32 s43, s43, 0
	s_mov_b32 m0, s60
	s_nop 0
	global_load_lds_dwordx4 v144, s[46:47]
	s_mov_b32 m0, s61
	s_nop 0
	global_load_lds_dwordx4 v140, s[46:47]
	s_add_i32 m0, s56, 0xc000
	s_nop 0
	global_load_lds_dwordx4 v144, s[42:43]
	s_add_i32 m0, s56, 0xe000
	s_nop 0
	global_load_lds_dwordx4 v140, s[42:43]
	ds_read_b128 v[190:193], v132
	ds_read_b128 v[194:197], v132 offset:1024
	ds_read_b128 v[198:201], v132 offset:2048
	ds_read_b128 v[202:205], v132 offset:3072
	ds_read_b128 v[206:209], v132 offset:4096
	ds_read_b128 v[210:213], v132 offset:5120
	ds_read_b128 v[214:217], v132 offset:6144
	ds_read_b128 v[218:221], v132 offset:7168
	s_waitcnt vmcnt(8)
	s_waitcnt lgkmcnt(8)
	s_barrier
	s_setprio 1
	s_waitcnt lgkmcnt(0)
	v_mfma_f32_16x16x32_bf16 v[128:131], v[146:149], v[190:193], v[128:131]
	v_mfma_f32_16x16x32_bf16 v[124:127], v[154:157], v[190:193], v[124:127]
	v_mfma_f32_16x16x32_bf16 v[112:115], v[146:149], v[198:201], v[112:115]
	v_mfma_f32_16x16x32_bf16 v[108:111], v[154:157], v[198:201], v[108:111]
	v_mfma_f32_16x16x32_bf16 v[96:99], v[146:149], v[206:209], v[96:99]
	v_mfma_f32_16x16x32_bf16 v[92:95], v[154:157], v[206:209], v[92:95]
	v_mfma_f32_16x16x32_bf16 v[80:83], v[146:149], v[214:217], v[80:83]
	v_mfma_f32_16x16x32_bf16 v[76:79], v[154:157], v[214:217], v[76:79]
	v_mfma_f32_16x16x32_bf16 v[128:131], v[150:153], v[194:197], v[128:131]
	v_mfma_f32_16x16x32_bf16 v[124:127], v[158:161], v[194:197], v[124:127]
	v_mfma_f32_16x16x32_bf16 v[112:115], v[150:153], v[202:205], v[112:115]
	v_mfma_f32_16x16x32_bf16 v[108:111], v[158:161], v[202:205], v[108:111]
	v_mfma_f32_16x16x32_bf16 v[96:99], v[150:153], v[210:213], v[96:99]
	v_mfma_f32_16x16x32_bf16 v[92:95], v[158:161], v[210:213], v[92:95]
	v_mfma_f32_16x16x32_bf16 v[80:83], v[150:153], v[218:221], v[80:83]
	v_mfma_f32_16x16x32_bf16 v[76:79], v[158:161], v[218:221], v[76:79]
	s_setprio 0
	s_setprio 1
	v_mfma_f32_16x16x32_bf16 v[120:123], v[162:165], v[190:193], v[120:123]
	v_mfma_f32_16x16x32_bf16 v[116:119], v[170:173], v[190:193], v[116:119]
	v_mfma_f32_16x16x32_bf16 v[104:107], v[162:165], v[198:201], v[104:107]
	v_mfma_f32_16x16x32_bf16 v[100:103], v[170:173], v[198:201], v[100:103]
	v_mfma_f32_16x16x32_bf16 v[88:91], v[162:165], v[206:209], v[88:91]
	v_mfma_f32_16x16x32_bf16 v[84:87], v[170:173], v[206:209], v[84:87]
	v_mfma_f32_16x16x32_bf16 v[72:75], v[162:165], v[214:217], v[72:75]
	v_mfma_f32_16x16x32_bf16 v[68:71], v[170:173], v[214:217], v[68:71]
	v_mfma_f32_16x16x32_bf16 v[120:123], v[166:169], v[194:197], v[120:123]
	v_mfma_f32_16x16x32_bf16 v[116:119], v[186:189], v[194:197], v[116:119]
	v_mfma_f32_16x16x32_bf16 v[104:107], v[166:169], v[202:205], v[104:107]
	v_mfma_f32_16x16x32_bf16 v[100:103], v[186:189], v[202:205], v[100:103]
	v_mfma_f32_16x16x32_bf16 v[88:91], v[166:169], v[210:213], v[88:91]
	v_mfma_f32_16x16x32_bf16 v[84:87], v[186:189], v[210:213], v[84:87]
	v_mfma_f32_16x16x32_bf16 v[72:75], v[166:169], v[218:221], v[72:75]
	v_mfma_f32_16x16x32_bf16 v[68:71], v[186:189], v[218:221], v[68:71]
	s_setprio 0
	s_barrier
	s_add_i32 s42, s64, s69
	s_mov_b32 m0, s42
	s_nop 0
	global_load_lds_dwordx4 v142, s[48:49]
	s_add_i32 m0, s42, 0x2000
	s_add_u32 s42, s48, 0x40000
	s_addc_u32 s43, s49, 0
	s_add_i32 s64, s65, s69
	global_load_lds_dwordx4 v0, s[48:49]
	s_mov_b32 m0, s64
	s_nop 0
	global_load_lds_dwordx4 v142, s[42:43]
	s_add_i32 m0, s64, 0x2000
	s_nop 0
	global_load_lds_dwordx4 v0, s[42:43]
	ds_read_b128 v[190:193], v132 offset:16384
	ds_read_b128 v[194:197], v132 offset:17408
	ds_read_b128 v[198:201], v132 offset:18432
	ds_read_b128 v[202:205], v132 offset:19456
	ds_read_b128 v[206:209], v132 offset:20480
	ds_read_b128 v[210:213], v132 offset:21504
	ds_read_b128 v[214:217], v132 offset:22528
	ds_read_b128 v[218:221], v132 offset:23552
	s_waitcnt vmcnt(6)
	s_waitcnt lgkmcnt(0)
	s_barrier
	s_setprio 1
	s_waitcnt lgkmcnt(0)
	v_mfma_f32_16x16x32_bf16 v[64:67], v[146:149], v[190:193], v[64:67]
	v_mfma_f32_16x16x32_bf16 v[60:63], v[154:157], v[190:193], v[60:63]
	v_mfma_f32_16x16x32_bf16 v[48:51], v[146:149], v[198:201], v[48:51]
	v_mfma_f32_16x16x32_bf16 v[44:47], v[154:157], v[198:201], v[44:47]
	v_mfma_f32_16x16x32_bf16 v[32:35], v[146:149], v[206:209], v[32:35]
	v_mfma_f32_16x16x32_bf16 v[28:31], v[154:157], v[206:209], v[28:31]
	v_mfma_f32_16x16x32_bf16 v[16:19], v[146:149], v[214:217], v[16:19]
	v_mfma_f32_16x16x32_bf16 v[12:15], v[154:157], v[214:217], v[12:15]
	v_mfma_f32_16x16x32_bf16 v[64:67], v[150:153], v[194:197], v[64:67]
	v_mfma_f32_16x16x32_bf16 v[60:63], v[158:161], v[194:197], v[60:63]
	v_mfma_f32_16x16x32_bf16 v[48:51], v[150:153], v[202:205], v[48:51]
	v_mfma_f32_16x16x32_bf16 v[44:47], v[158:161], v[202:205], v[44:47]
	v_mfma_f32_16x16x32_bf16 v[32:35], v[150:153], v[210:213], v[32:35]
	v_mfma_f32_16x16x32_bf16 v[28:31], v[158:161], v[210:213], v[28:31]
	v_mfma_f32_16x16x32_bf16 v[16:19], v[150:153], v[218:221], v[16:19]
	v_mfma_f32_16x16x32_bf16 v[12:15], v[158:161], v[218:221], v[12:15]
	s_setprio 0
	s_setprio 1
	v_mfma_f32_16x16x32_bf16 v[56:59], v[162:165], v[190:193], v[56:59]
	v_mfma_f32_16x16x32_bf16 v[52:55], v[170:173], v[190:193], v[52:55]
	v_mfma_f32_16x16x32_bf16 v[40:43], v[162:165], v[198:201], v[40:43]
	v_mfma_f32_16x16x32_bf16 v[36:39], v[170:173], v[198:201], v[36:39]
	v_mfma_f32_16x16x32_bf16 v[24:27], v[162:165], v[206:209], v[24:27]
	v_mfma_f32_16x16x32_bf16 v[20:23], v[170:173], v[206:209], v[20:23]
	v_mfma_f32_16x16x32_bf16 v[8:11], v[162:165], v[214:217], v[8:11]
	v_mfma_f32_16x16x32_bf16 v[4:7], v[170:173], v[214:217], v[4:7]
	v_mfma_f32_16x16x32_bf16 v[56:59], v[166:169], v[194:197], v[56:59]
	v_mfma_f32_16x16x32_bf16 v[52:55], v[186:189], v[194:197], v[52:55]
	v_mfma_f32_16x16x32_bf16 v[40:43], v[166:169], v[202:205], v[40:43]
	v_mfma_f32_16x16x32_bf16 v[36:39], v[186:189], v[202:205], v[36:39]
	v_mfma_f32_16x16x32_bf16 v[24:27], v[166:169], v[210:213], v[24:27]
	v_mfma_f32_16x16x32_bf16 v[20:23], v[186:189], v[210:213], v[20:23]
	v_mfma_f32_16x16x32_bf16 v[8:11], v[166:169], v[218:221], v[8:11]
	v_mfma_f32_16x16x32_bf16 v[4:7], v[186:189], v[218:221], v[4:7]
	s_setprio 0
	s_barrier
	s_add_i32 s64, 0, 0x18000
	v_add_u32_e32 v138, s64, v3
	s_add_i32 s65, 0, 0x1c000
	ds_read_b128 v[146:149], v138
	ds_read_b128 v[150:153], v138 offset:1024
	ds_read_b128 v[154:157], v138 offset:2048
	ds_read_b128 v[158:161], v138 offset:3072
	v_add_u32_e32 v138, s65, v3
	ds_read_b128 v[162:165], v138
	ds_read_b128 v[166:169], v138 offset:1024
	ds_read_b128 v[170:173], v138 offset:2048
	ds_read_b128 v[186:189], v138 offset:3072
	s_add_u32 s42, s50, 0x40000
	s_addc_u32 s43, s51, 0
	s_mov_b32 m0, s56
	s_nop 0
	global_load_lds_dwordx4 v144, s[50:51]
	s_mov_b32 m0, s57
	s_nop 0
	global_load_lds_dwordx4 v140, s[50:51]
	s_mov_b32 m0, s58
	s_nop 0
	global_load_lds_dwordx4 v144, s[42:43]
	s_mov_b32 m0, s59
	s_nop 0
	global_load_lds_dwordx4 v140, s[42:43]
	ds_read_b128 v[190:193], v132 offset:32768
	ds_read_b128 v[194:197], v132 offset:33792
	ds_read_b128 v[198:201], v132 offset:34816
	ds_read_b128 v[202:205], v132 offset:35840
	ds_read_b128 v[206:209], v132 offset:36864
	ds_read_b128 v[210:213], v132 offset:37888
	ds_read_b128 v[214:217], v132 offset:38912
	ds_read_b128 v[218:221], v132 offset:39936
	s_waitcnt vmcnt(8)
	s_waitcnt lgkmcnt(8)
	s_barrier
	s_setprio 1
	s_waitcnt lgkmcnt(0)
	v_mfma_f32_16x16x32_bf16 v[128:131], v[146:149], v[190:193], v[128:131]
	v_mfma_f32_16x16x32_bf16 v[124:127], v[154:157], v[190:193], v[124:127]
	v_mfma_f32_16x16x32_bf16 v[112:115], v[146:149], v[198:201], v[112:115]
	v_mfma_f32_16x16x32_bf16 v[108:111], v[154:157], v[198:201], v[108:111]
	v_mfma_f32_16x16x32_bf16 v[96:99], v[146:149], v[206:209], v[96:99]
	v_mfma_f32_16x16x32_bf16 v[92:95], v[154:157], v[206:209], v[92:95]
	v_mfma_f32_16x16x32_bf16 v[80:83], v[146:149], v[214:217], v[80:83]
	v_mfma_f32_16x16x32_bf16 v[76:79], v[154:157], v[214:217], v[76:79]
	v_mfma_f32_16x16x32_bf16 v[128:131], v[150:153], v[194:197], v[128:131]
	v_mfma_f32_16x16x32_bf16 v[124:127], v[158:161], v[194:197], v[124:127]
	v_mfma_f32_16x16x32_bf16 v[112:115], v[150:153], v[202:205], v[112:115]
	v_mfma_f32_16x16x32_bf16 v[108:111], v[158:161], v[202:205], v[108:111]
	v_mfma_f32_16x16x32_bf16 v[96:99], v[150:153], v[210:213], v[96:99]
	v_mfma_f32_16x16x32_bf16 v[92:95], v[158:161], v[210:213], v[92:95]
	v_mfma_f32_16x16x32_bf16 v[80:83], v[150:153], v[218:221], v[80:83]
	v_mfma_f32_16x16x32_bf16 v[76:79], v[158:161], v[218:221], v[76:79]
	s_setprio 0
	s_setprio 1
	v_mfma_f32_16x16x32_bf16 v[120:123], v[162:165], v[190:193], v[120:123]
	v_mfma_f32_16x16x32_bf16 v[116:119], v[170:173], v[190:193], v[116:119]
	v_mfma_f32_16x16x32_bf16 v[104:107], v[162:165], v[198:201], v[104:107]
	v_mfma_f32_16x16x32_bf16 v[100:103], v[170:173], v[198:201], v[100:103]
	v_mfma_f32_16x16x32_bf16 v[88:91], v[162:165], v[206:209], v[88:91]
	v_mfma_f32_16x16x32_bf16 v[84:87], v[170:173], v[206:209], v[84:87]
	v_mfma_f32_16x16x32_bf16 v[72:75], v[162:165], v[214:217], v[72:75]
	v_mfma_f32_16x16x32_bf16 v[68:71], v[170:173], v[214:217], v[68:71]
	v_mfma_f32_16x16x32_bf16 v[120:123], v[166:169], v[194:197], v[120:123]
	v_mfma_f32_16x16x32_bf16 v[116:119], v[186:189], v[194:197], v[116:119]
	v_mfma_f32_16x16x32_bf16 v[104:107], v[166:169], v[202:205], v[104:107]
	v_mfma_f32_16x16x32_bf16 v[100:103], v[186:189], v[202:205], v[100:103]
	v_mfma_f32_16x16x32_bf16 v[88:91], v[166:169], v[210:213], v[88:91]
	v_mfma_f32_16x16x32_bf16 v[84:87], v[186:189], v[210:213], v[84:87]
	v_mfma_f32_16x16x32_bf16 v[72:75], v[166:169], v[218:221], v[72:75]
	v_mfma_f32_16x16x32_bf16 v[68:71], v[186:189], v[218:221], v[68:71]
	s_setprio 0
	s_barrier
	s_add_u32 s42, s48, 0x80
	s_addc_u32 s43, s49, 0
	s_add_i32 s50, s64, s69
	s_mov_b32 m0, s50
	s_nop 0
	global_load_lds_dwordx4 v142, s[42:43]
	s_add_i32 m0, s50, 0x2000
	s_nop 0
	global_load_lds_dwordx4 v0, s[42:43]
	s_add_u32 s42, s48, 0x40080
	s_addc_u32 s43, s49, 0
	s_add_i32 s48, s65, s69
	s_mov_b32 m0, s48
	s_nop 0
	global_load_lds_dwordx4 v142, s[42:43]
	s_add_i32 m0, s48, 0x2000
	s_nop 0
	global_load_lds_dwordx4 v0, s[42:43]
	ds_read_b128 v[190:193], v132 offset:49152
	ds_read_b128 v[194:197], v132 offset:50176
	ds_read_b128 v[198:201], v132 offset:51200
	ds_read_b128 v[202:205], v132 offset:52224
	ds_read_b128 v[206:209], v132 offset:53248
	ds_read_b128 v[210:213], v132 offset:54272
	ds_read_b128 v[214:217], v132 offset:55296
	ds_read_b128 v[218:221], v132 offset:56320
	s_waitcnt vmcnt(6)
	s_waitcnt lgkmcnt(0)
	s_barrier
	s_setprio 1
	s_waitcnt lgkmcnt(0)
	v_mfma_f32_16x16x32_bf16 v[64:67], v[146:149], v[190:193], v[64:67]
	v_mfma_f32_16x16x32_bf16 v[60:63], v[154:157], v[190:193], v[60:63]
	v_mfma_f32_16x16x32_bf16 v[48:51], v[146:149], v[198:201], v[48:51]
	v_mfma_f32_16x16x32_bf16 v[44:47], v[154:157], v[198:201], v[44:47]
	v_mfma_f32_16x16x32_bf16 v[32:35], v[146:149], v[206:209], v[32:35]
	v_mfma_f32_16x16x32_bf16 v[28:31], v[154:157], v[206:209], v[28:31]
	v_mfma_f32_16x16x32_bf16 v[16:19], v[146:149], v[214:217], v[16:19]
	v_mfma_f32_16x16x32_bf16 v[12:15], v[154:157], v[214:217], v[12:15]
	v_mfma_f32_16x16x32_bf16 v[64:67], v[150:153], v[194:197], v[64:67]
	v_mfma_f32_16x16x32_bf16 v[60:63], v[158:161], v[194:197], v[60:63]
	v_mfma_f32_16x16x32_bf16 v[48:51], v[150:153], v[202:205], v[48:51]
	v_mfma_f32_16x16x32_bf16 v[44:47], v[158:161], v[202:205], v[44:47]
	v_mfma_f32_16x16x32_bf16 v[32:35], v[150:153], v[210:213], v[32:35]
	v_mfma_f32_16x16x32_bf16 v[28:31], v[158:161], v[210:213], v[28:31]
	v_mfma_f32_16x16x32_bf16 v[16:19], v[150:153], v[218:221], v[16:19]
	v_mfma_f32_16x16x32_bf16 v[12:15], v[158:161], v[218:221], v[12:15]
	s_setprio 0
	s_setprio 1
	v_mfma_f32_16x16x32_bf16 v[56:59], v[162:165], v[190:193], v[56:59]
	v_mfma_f32_16x16x32_bf16 v[52:55], v[170:173], v[190:193], v[52:55]
	v_mfma_f32_16x16x32_bf16 v[40:43], v[162:165], v[198:201], v[40:43]
	v_mfma_f32_16x16x32_bf16 v[36:39], v[170:173], v[198:201], v[36:39]
	v_mfma_f32_16x16x32_bf16 v[24:27], v[162:165], v[206:209], v[24:27]
	v_mfma_f32_16x16x32_bf16 v[20:23], v[170:173], v[206:209], v[20:23]
	v_mfma_f32_16x16x32_bf16 v[8:11], v[162:165], v[214:217], v[8:11]
	v_mfma_f32_16x16x32_bf16 v[4:7], v[170:173], v[214:217], v[4:7]
	v_mfma_f32_16x16x32_bf16 v[56:59], v[166:169], v[194:197], v[56:59]
	v_mfma_f32_16x16x32_bf16 v[52:55], v[186:189], v[194:197], v[52:55]
	v_mfma_f32_16x16x32_bf16 v[40:43], v[166:169], v[202:205], v[40:43]
	v_mfma_f32_16x16x32_bf16 v[36:39], v[186:189], v[202:205], v[36:39]
	v_mfma_f32_16x16x32_bf16 v[24:27], v[166:169], v[210:213], v[24:27]
	v_mfma_f32_16x16x32_bf16 v[20:23], v[186:189], v[210:213], v[20:23]
	v_mfma_f32_16x16x32_bf16 v[8:11], v[166:169], v[218:221], v[8:11]
	v_mfma_f32_16x16x32_bf16 v[4:7], v[186:189], v[218:221], v[4:7]
	s_setprio 0
	s_barrier
	s_add_i32 s63, s63, 2
	s_add_u32 s28, s28, 0x100
	s_addc_u32 s29, s29, 0
	s_cmp_gt_u32 s63, 13
	s_mov_b64 s[42:43], s[44:45]
	s_cbranch_scc0 .LBB0_500
	s_and_b64 vcc, exec, s[14:15]
	s_cbranch_vccz .LBB0_503
	s_barrier
